# att7 + P1 K-loop first iteration peeled with relaxed vmcnt(24) on its first two waits (loads older than epilogue stores)
# baseline (speedup 1.0000x reference)
.LBB0_216:
	s_ashr_i32 s31, s30, 31
	s_lshl_b64 s[24:25], s[30:31], 19
	s_add_u32 s36, s20, s24
	s_addc_u32 s37, s21, s25
	s_and_b64 s[24:25], s[2:3], exec
	s_cselect_b32 s24, s37, s1
	s_cselect_b32 s25, s36, s0
	s_ashr_i32 s15, s14, 31
	s_lshl_b64 s[38:39], s[14:15], 19
	s_add_u32 s38, s6, s38
	s_addc_u32 s39, s7, s39
	s_and_b64 s[48:49], s[2:3], exec
	s_cselect_b32 s15, s39, s55
	s_cselect_b32 s31, s38, s54
	s_add_u32 s48, s0, 0x40080
	s_addc_u32 s49, s1, 0
	s_add_u32 s56, s54, 0x100
	v_mov_b32_e32 v0, 0
	s_addc_u32 s57, s55, 0
	s_mov_b32 s62, -2
	v_mov_b32_e32 v1, v0
	v_mov_b32_e32 v2, v0
	v_mov_b32_e32 v3, v0
	v_mov_b32_e32 v4, v0
	v_mov_b32_e32 v5, v0
	v_mov_b32_e32 v6, v0
	v_mov_b32_e32 v7, v0
	v_mov_b32_e32 v12, v0
	v_mov_b32_e32 v13, v0
	v_mov_b32_e32 v14, v0
	v_mov_b32_e32 v15, v0
	v_mov_b32_e32 v20, v0
	v_mov_b32_e32 v21, v0
	v_mov_b32_e32 v22, v0
	v_mov_b32_e32 v23, v0
	v_mov_b32_e32 v28, v0
	v_mov_b32_e32 v29, v0
	v_mov_b32_e32 v30, v0
	v_mov_b32_e32 v31, v0
	v_mov_b32_e32 v36, v0
	v_mov_b32_e32 v37, v0
	v_mov_b32_e32 v38, v0
	v_mov_b32_e32 v39, v0
	v_mov_b32_e32 v44, v0
	v_mov_b32_e32 v45, v0
	v_mov_b32_e32 v46, v0
	v_mov_b32_e32 v47, v0
	v_mov_b32_e32 v52, v0
	v_mov_b32_e32 v53, v0
	v_mov_b32_e32 v54, v0
	v_mov_b32_e32 v55, v0
	v_mov_b32_e32 v8, v0
	v_mov_b32_e32 v9, v0
	v_mov_b32_e32 v10, v0
	v_mov_b32_e32 v11, v0
	v_mov_b32_e32 v16, v0
	v_mov_b32_e32 v17, v0
	v_mov_b32_e32 v18, v0
	v_mov_b32_e32 v19, v0
	v_mov_b32_e32 v24, v0
	v_mov_b32_e32 v25, v0
	v_mov_b32_e32 v26, v0
	v_mov_b32_e32 v27, v0
	v_mov_b32_e32 v32, v0
	v_mov_b32_e32 v33, v0
	v_mov_b32_e32 v34, v0
	v_mov_b32_e32 v35, v0
	v_mov_b32_e32 v40, v0
	v_mov_b32_e32 v41, v0
	v_mov_b32_e32 v42, v0
	v_mov_b32_e32 v43, v0
	v_mov_b32_e32 v48, v0
	v_mov_b32_e32 v49, v0
	v_mov_b32_e32 v50, v0
	v_mov_b32_e32 v51, v0
	v_mov_b32_e32 v56, v0
	v_mov_b32_e32 v57, v0
	v_mov_b32_e32 v58, v0
	v_mov_b32_e32 v59, v0
	v_mov_b32_e32 v60, v0
	v_mov_b32_e32 v61, v0
	v_mov_b32_e32 v62, v0
	v_mov_b32_e32 v63, v0
	v_mov_b32_e32 v64, v0
	v_mov_b32_e32 v65, v0
	v_mov_b32_e32 v66, v0
	v_mov_b32_e32 v67, v0
	v_mov_b32_e32 v68, v0
	v_mov_b32_e32 v69, v0
	v_mov_b32_e32 v70, v0
	v_mov_b32_e32 v71, v0
	v_mov_b32_e32 v76, v0
	v_mov_b32_e32 v77, v0
	v_mov_b32_e32 v78, v0
	v_mov_b32_e32 v79, v0
	v_mov_b32_e32 v84, v0
	v_mov_b32_e32 v85, v0
	v_mov_b32_e32 v86, v0
	v_mov_b32_e32 v87, v0
	v_mov_b32_e32 v92, v0
	v_mov_b32_e32 v93, v0
	v_mov_b32_e32 v94, v0
	v_mov_b32_e32 v95, v0
	v_mov_b32_e32 v100, v0
	v_mov_b32_e32 v101, v0
	v_mov_b32_e32 v102, v0
	v_mov_b32_e32 v103, v0
	v_mov_b32_e32 v108, v0
	v_mov_b32_e32 v109, v0
	v_mov_b32_e32 v110, v0
	v_mov_b32_e32 v111, v0
	v_mov_b32_e32 v116, v0
	v_mov_b32_e32 v117, v0
	v_mov_b32_e32 v118, v0
	v_mov_b32_e32 v119, v0
	v_mov_b32_e32 v72, v0
	v_mov_b32_e32 v73, v0
	v_mov_b32_e32 v74, v0
	v_mov_b32_e32 v75, v0
	v_mov_b32_e32 v80, v0
	v_mov_b32_e32 v81, v0
	v_mov_b32_e32 v82, v0
	v_mov_b32_e32 v83, v0
	v_mov_b32_e32 v88, v0
	v_mov_b32_e32 v89, v0
	v_mov_b32_e32 v90, v0
	v_mov_b32_e32 v91, v0
	v_mov_b32_e32 v96, v0
	v_mov_b32_e32 v97, v0
	v_mov_b32_e32 v98, v0
	v_mov_b32_e32 v99, v0
	v_mov_b32_e32 v104, v0
	v_mov_b32_e32 v105, v0
	v_mov_b32_e32 v106, v0
	v_mov_b32_e32 v107, v0
	v_mov_b32_e32 v112, v0
	v_mov_b32_e32 v113, v0
	v_mov_b32_e32 v114, v0
	v_mov_b32_e32 v115, v0
	v_mov_b32_e32 v120, v0
	v_mov_b32_e32 v121, v0
	v_mov_b32_e32 v122, v0
	v_mov_b32_e32 v123, v0
	v_mov_b32_e32 v124, v0
	v_mov_b32_e32 v125, v0
	v_mov_b32_e32 v126, v0
	v_mov_b32_e32 v127, v0
	ds_read_b128 v[154:157], v149
	ds_read_b128 v[158:161], v149 offset:1024
	ds_read_b128 v[162:165], v149 offset:2048
	ds_read_b128 v[166:169], v149 offset:3072
	ds_read_b128 v[170:173], v150
	ds_read_b128 v[174:177], v150 offset:1024
	ds_read_b128 v[178:181], v150 offset:2048
	ds_read_b128 v[182:185], v150 offset:3072
	s_add_u32 s0, s48, 0xfffc0080
	s_addc_u32 s1, s49, -1
	s_cmp_eq_u32 s62, 12
	s_cselect_b32 s55, s24, s1
	s_cselect_b32 s54, s25, s0
	s_cselect_b32 s1, s15, s57
	s_cselect_b32 s0, s31, s56
	v_lshl_add_u64 v[218:219], s[48:49], 0, v[136:137]
	s_add_i32 m0, s26, 0xc000
	ds_read_b128 v[186:189], v151
	ds_read_b128 v[190:193], v151 offset:1024
	ds_read_b128 v[194:197], v151 offset:2048
	ds_read_b128 v[198:201], v151 offset:3072
	ds_read_b128 v[202:205], v151 offset:4096
	ds_read_b128 v[206:209], v151 offset:5120
	ds_read_b128 v[210:213], v151 offset:6144
	ds_read_b128 v[214:217], v151 offset:7168
	global_load_lds_dwordx4 v[218:219], off
	v_lshl_add_u64 v[218:219], s[48:49], 0, v[138:139]
	s_add_i32 m0, s26, 0xe000
	s_nop 0
	global_load_lds_dwordx4 v[218:219], off
	s_waitcnt vmcnt(24)
	s_waitcnt lgkmcnt(0)
	s_barrier
	s_setprio 1
	s_waitcnt lgkmcnt(0)
	v_mfma_f32_16x16x32_bf16 v[124:127], v[154:157], v[186:189], v[124:127]
	v_mfma_f32_16x16x32_bf16 v[120:123], v[162:165], v[186:189], v[120:123]
	v_mfma_f32_16x16x32_bf16 v[112:115], v[154:157], v[194:197], v[112:115]
	v_mfma_f32_16x16x32_bf16 v[104:107], v[162:165], v[194:197], v[104:107]
	v_mfma_f32_16x16x32_bf16 v[96:99], v[154:157], v[202:205], v[96:99]
	v_mfma_f32_16x16x32_bf16 v[88:91], v[162:165], v[202:205], v[88:91]
	v_mfma_f32_16x16x32_bf16 v[80:83], v[154:157], v[210:213], v[80:83]
	v_mfma_f32_16x16x32_bf16 v[72:75], v[162:165], v[210:213], v[72:75]
	v_mfma_f32_16x16x32_bf16 v[124:127], v[158:161], v[190:193], v[124:127]
	v_mfma_f32_16x16x32_bf16 v[120:123], v[166:169], v[190:193], v[120:123]
	v_mfma_f32_16x16x32_bf16 v[112:115], v[158:161], v[198:201], v[112:115]
	v_mfma_f32_16x16x32_bf16 v[104:107], v[166:169], v[198:201], v[104:107]
	v_mfma_f32_16x16x32_bf16 v[96:99], v[158:161], v[206:209], v[96:99]
	v_mfma_f32_16x16x32_bf16 v[88:91], v[166:169], v[206:209], v[88:91]
	v_mfma_f32_16x16x32_bf16 v[80:83], v[158:161], v[214:217], v[80:83]
	v_mfma_f32_16x16x32_bf16 v[72:75], v[166:169], v[214:217], v[72:75]
	s_setprio 0
	s_setprio 1
	v_mfma_f32_16x16x32_bf16 v[116:119], v[170:173], v[186:189], v[116:119]
	v_mfma_f32_16x16x32_bf16 v[108:111], v[178:181], v[186:189], v[108:111]
	v_mfma_f32_16x16x32_bf16 v[100:103], v[170:173], v[194:197], v[100:103]
	v_mfma_f32_16x16x32_bf16 v[92:95], v[178:181], v[194:197], v[92:95]
	v_mfma_f32_16x16x32_bf16 v[84:87], v[170:173], v[202:205], v[84:87]
	v_mfma_f32_16x16x32_bf16 v[76:79], v[178:181], v[202:205], v[76:79]
	v_mfma_f32_16x16x32_bf16 v[68:71], v[170:173], v[210:213], v[68:71]
	v_mfma_f32_16x16x32_bf16 v[64:67], v[178:181], v[210:213], v[64:67]
	v_mfma_f32_16x16x32_bf16 v[116:119], v[174:177], v[190:193], v[116:119]
	v_mfma_f32_16x16x32_bf16 v[108:111], v[182:185], v[190:193], v[108:111]
	v_mfma_f32_16x16x32_bf16 v[100:103], v[174:177], v[198:201], v[100:103]
	v_mfma_f32_16x16x32_bf16 v[92:95], v[182:185], v[198:201], v[92:95]
	v_mfma_f32_16x16x32_bf16 v[84:87], v[174:177], v[206:209], v[84:87]
	v_mfma_f32_16x16x32_bf16 v[76:79], v[182:185], v[206:209], v[76:79]
	v_mfma_f32_16x16x32_bf16 v[68:71], v[174:177], v[214:217], v[68:71]
	v_mfma_f32_16x16x32_bf16 v[64:67], v[182:185], v[214:217], v[64:67]
	s_setprio 0
	s_barrier
	s_add_i32 s63, s47, s17
	v_lshl_add_u64 v[218:219], s[0:1], 0, v[132:133]
	s_mov_b32 m0, s63
	ds_read_b128 v[186:189], v151 offset:16384
	ds_read_b128 v[190:193], v151 offset:17408
	ds_read_b128 v[194:197], v151 offset:18432
	ds_read_b128 v[198:201], v151 offset:19456
	ds_read_b128 v[202:205], v151 offset:20480
	ds_read_b128 v[206:209], v151 offset:21504
	ds_read_b128 v[210:213], v151 offset:22528
	ds_read_b128 v[214:217], v151 offset:23552
	global_load_lds_dwordx4 v[218:219], off
	s_add_i32 m0, s63, 0x2000
	s_add_u32 s66, s0, 0x40000
	v_lshl_add_u64 v[220:221], s[0:1], 0, v[128:129]
	s_addc_u32 s67, s1, 0
	s_add_i32 s63, s50, s17
	global_load_lds_dwordx4 v[220:221], off
	v_lshl_add_u64 v[222:223], s[66:67], 0, v[132:133]
	s_mov_b32 m0, s63
	v_lshl_add_u64 v[224:225], s[54:55], 0, v[130:131]
	global_load_lds_dwordx4 v[222:223], off
	v_lshl_add_u64 v[222:223], s[66:67], 0, v[128:129]
	s_add_i32 m0, s63, 0x2000
	s_nop 0
	global_load_lds_dwordx4 v[222:223], off
	v_lshl_add_u64 v[222:223], s[54:55], 0, v[134:135]
	s_mov_b32 m0, s26
	s_nop 0
	global_load_lds_dwordx4 v[222:223], off
	s_mov_b32 m0, s27
	s_nop 0
	global_load_lds_dwordx4 v[224:225], off
	s_waitcnt vmcnt(24)
	s_waitcnt lgkmcnt(0)
	s_barrier
	s_setprio 1
	s_waitcnt lgkmcnt(0)
	v_mfma_f32_16x16x32_bf16 v[60:63], v[154:157], v[186:189], v[60:63]
	v_mfma_f32_16x16x32_bf16 v[56:59], v[162:165], v[186:189], v[56:59]
	v_mfma_f32_16x16x32_bf16 v[48:51], v[154:157], v[194:197], v[48:51]
	v_mfma_f32_16x16x32_bf16 v[40:43], v[162:165], v[194:197], v[40:43]
	v_mfma_f32_16x16x32_bf16 v[32:35], v[154:157], v[202:205], v[32:35]
	v_mfma_f32_16x16x32_bf16 v[24:27], v[162:165], v[202:205], v[24:27]
	v_mfma_f32_16x16x32_bf16 v[16:19], v[154:157], v[210:213], v[16:19]
	v_mfma_f32_16x16x32_bf16 v[8:11], v[162:165], v[210:213], v[8:11]
	v_mfma_f32_16x16x32_bf16 v[60:63], v[158:161], v[190:193], v[60:63]
	v_mfma_f32_16x16x32_bf16 v[56:59], v[166:169], v[190:193], v[56:59]
	v_mfma_f32_16x16x32_bf16 v[48:51], v[158:161], v[198:201], v[48:51]
	v_mfma_f32_16x16x32_bf16 v[40:43], v[166:169], v[198:201], v[40:43]
	v_mfma_f32_16x16x32_bf16 v[32:35], v[158:161], v[206:209], v[32:35]
	v_mfma_f32_16x16x32_bf16 v[24:27], v[166:169], v[206:209], v[24:27]
	v_mfma_f32_16x16x32_bf16 v[16:19], v[158:161], v[214:217], v[16:19]
	v_mfma_f32_16x16x32_bf16 v[8:11], v[166:169], v[214:217], v[8:11]
	s_setprio 0
	s_setprio 1
	v_mfma_f32_16x16x32_bf16 v[52:55], v[170:173], v[186:189], v[52:55]
	v_mfma_f32_16x16x32_bf16 v[44:47], v[178:181], v[186:189], v[44:47]
	v_mfma_f32_16x16x32_bf16 v[36:39], v[170:173], v[194:197], v[36:39]
	v_mfma_f32_16x16x32_bf16 v[28:31], v[178:181], v[194:197], v[28:31]
	v_mfma_f32_16x16x32_bf16 v[20:23], v[170:173], v[202:205], v[20:23]
	v_mfma_f32_16x16x32_bf16 v[12:15], v[178:181], v[202:205], v[12:15]
	v_mfma_f32_16x16x32_bf16 v[4:7], v[170:173], v[210:213], v[4:7]
	v_mfma_f32_16x16x32_bf16 v[0:3], v[178:181], v[210:213], v[0:3]
	v_mfma_f32_16x16x32_bf16 v[52:55], v[174:177], v[190:193], v[52:55]
	v_mfma_f32_16x16x32_bf16 v[44:47], v[182:185], v[190:193], v[44:47]
	v_mfma_f32_16x16x32_bf16 v[36:39], v[174:177], v[198:201], v[36:39]
	v_mfma_f32_16x16x32_bf16 v[28:31], v[182:185], v[198:201], v[28:31]
	v_mfma_f32_16x16x32_bf16 v[20:23], v[174:177], v[206:209], v[20:23]
	v_mfma_f32_16x16x32_bf16 v[12:15], v[182:185], v[206:209], v[12:15]
	v_mfma_f32_16x16x32_bf16 v[4:7], v[174:177], v[214:217], v[4:7]
	v_mfma_f32_16x16x32_bf16 v[0:3], v[182:185], v[214:217], v[0:3]
	s_setprio 0
	s_barrier
	s_add_i32 s63, 0, 0x18000
	v_add_u32_e32 v144, s63, v147
	s_add_i32 s66, 0, 0x1c000
	ds_read_b128 v[154:157], v144
	ds_read_b128 v[158:161], v144 offset:1024
	ds_read_b128 v[162:165], v144 offset:2048
	ds_read_b128 v[166:169], v144 offset:3072
	v_add_u32_e32 v144, s66, v147
	ds_read_b128 v[170:173], v144
	ds_read_b128 v[174:177], v144 offset:1024
	ds_read_b128 v[178:181], v144 offset:2048
	ds_read_b128 v[182:185], v144 offset:3072
	s_add_u32 s54, s54, 0x40000
	s_addc_u32 s55, s55, 0
	s_mov_b32 m0, s33
	v_lshl_add_u64 v[226:227], s[54:55], 0, v[134:135]
	ds_read_b128 v[186:189], v151 offset:32768
	ds_read_b128 v[190:193], v151 offset:33792
	ds_read_b128 v[194:197], v151 offset:34816
	ds_read_b128 v[198:201], v151 offset:35840
	ds_read_b128 v[202:205], v151 offset:36864
	ds_read_b128 v[206:209], v151 offset:37888
	ds_read_b128 v[210:213], v151 offset:38912
	ds_read_b128 v[214:217], v151 offset:39936
	global_load_lds_dwordx4 v[226:227], off
	v_lshl_add_u64 v[226:227], s[54:55], 0, v[130:131]
	s_mov_b32 m0, s34
	s_nop 0
	global_load_lds_dwordx4 v[226:227], off
	s_waitcnt vmcnt(8)
	s_waitcnt lgkmcnt(0)
	s_barrier
	s_setprio 1
	s_waitcnt lgkmcnt(0)
	v_mfma_f32_16x16x32_bf16 v[124:127], v[154:157], v[186:189], v[124:127]
	v_mfma_f32_16x16x32_bf16 v[120:123], v[162:165], v[186:189], v[120:123]
	v_mfma_f32_16x16x32_bf16 v[112:115], v[154:157], v[194:197], v[112:115]
	v_mfma_f32_16x16x32_bf16 v[104:107], v[162:165], v[194:197], v[104:107]
	v_mfma_f32_16x16x32_bf16 v[96:99], v[154:157], v[202:205], v[96:99]
	v_mfma_f32_16x16x32_bf16 v[88:91], v[162:165], v[202:205], v[88:91]
	v_mfma_f32_16x16x32_bf16 v[80:83], v[154:157], v[210:213], v[80:83]
	v_mfma_f32_16x16x32_bf16 v[72:75], v[162:165], v[210:213], v[72:75]
	v_mfma_f32_16x16x32_bf16 v[124:127], v[158:161], v[190:193], v[124:127]
	v_mfma_f32_16x16x32_bf16 v[120:123], v[166:169], v[190:193], v[120:123]
	v_mfma_f32_16x16x32_bf16 v[112:115], v[158:161], v[198:201], v[112:115]
	v_mfma_f32_16x16x32_bf16 v[104:107], v[166:169], v[198:201], v[104:107]
	v_mfma_f32_16x16x32_bf16 v[96:99], v[158:161], v[206:209], v[96:99]
	v_mfma_f32_16x16x32_bf16 v[88:91], v[166:169], v[206:209], v[88:91]
	v_mfma_f32_16x16x32_bf16 v[80:83], v[158:161], v[214:217], v[80:83]
	v_mfma_f32_16x16x32_bf16 v[72:75], v[166:169], v[214:217], v[72:75]
	s_setprio 0
	s_setprio 1
	v_mfma_f32_16x16x32_bf16 v[116:119], v[170:173], v[186:189], v[116:119]
	v_mfma_f32_16x16x32_bf16 v[108:111], v[178:181], v[186:189], v[108:111]
	v_mfma_f32_16x16x32_bf16 v[100:103], v[170:173], v[194:197], v[100:103]
	v_mfma_f32_16x16x32_bf16 v[92:95], v[178:181], v[194:197], v[92:95]
	v_mfma_f32_16x16x32_bf16 v[84:87], v[170:173], v[202:205], v[84:87]
	v_mfma_f32_16x16x32_bf16 v[76:79], v[178:181], v[202:205], v[76:79]
	v_mfma_f32_16x16x32_bf16 v[68:71], v[170:173], v[210:213], v[68:71]
	v_mfma_f32_16x16x32_bf16 v[64:67], v[178:181], v[210:213], v[64:67]
	v_mfma_f32_16x16x32_bf16 v[116:119], v[174:177], v[190:193], v[116:119]
	v_mfma_f32_16x16x32_bf16 v[108:111], v[182:185], v[190:193], v[108:111]
	v_mfma_f32_16x16x32_bf16 v[100:103], v[174:177], v[198:201], v[100:103]
	v_mfma_f32_16x16x32_bf16 v[92:95], v[182:185], v[198:201], v[92:95]
	v_mfma_f32_16x16x32_bf16 v[84:87], v[174:177], v[206:209], v[84:87]
	v_mfma_f32_16x16x32_bf16 v[76:79], v[182:185], v[206:209], v[76:79]
	v_mfma_f32_16x16x32_bf16 v[68:71], v[174:177], v[214:217], v[68:71]
	v_mfma_f32_16x16x32_bf16 v[64:67], v[182:185], v[214:217], v[64:67]
	s_setprio 0
	s_barrier
	s_add_i32 s54, s63, s17
	v_lshl_add_u64 v[218:219], v[218:219], 0, s[10:11]
	s_mov_b32 m0, s54
	ds_read_b128 v[186:189], v151 offset:49152
	ds_read_b128 v[190:193], v151 offset:50176
	ds_read_b128 v[194:197], v151 offset:51200
	ds_read_b128 v[198:201], v151 offset:52224
	ds_read_b128 v[202:205], v151 offset:53248
	ds_read_b128 v[206:209], v151 offset:54272
	ds_read_b128 v[210:213], v151 offset:55296
	ds_read_b128 v[214:217], v151 offset:56320
	global_load_lds_dwordx4 v[218:219], off
	s_add_i32 m0, s54, 0x2000
	s_add_u32 s0, s0, 0x40080
	v_lshl_add_u64 v[218:219], v[220:221], 0, s[10:11]
	s_addc_u32 s1, s1, 0
	s_add_i32 s54, s66, s17
	global_load_lds_dwordx4 v[218:219], off
	v_lshl_add_u64 v[218:219], s[0:1], 0, v[132:133]
	s_mov_b32 m0, s54
	s_nop 0
	global_load_lds_dwordx4 v[218:219], off
	v_lshl_add_u64 v[218:219], s[0:1], 0, v[128:129]
	s_add_i32 m0, s54, 0x2000
	s_nop 0
	global_load_lds_dwordx4 v[218:219], off
	v_lshl_add_u64 v[218:219], v[222:223], 0, s[10:11]
	s_mov_b32 m0, s43
	s_nop 0
	global_load_lds_dwordx4 v[218:219], off
	v_lshl_add_u64 v[218:219], v[224:225], 0, s[10:11]
	s_mov_b32 m0, s44
	s_nop 0
	global_load_lds_dwordx4 v[218:219], off
	s_waitcnt vmcnt(8)
	s_waitcnt lgkmcnt(0)
	s_barrier
	s_setprio 1
	s_waitcnt lgkmcnt(0)
	v_mfma_f32_16x16x32_bf16 v[60:63], v[154:157], v[186:189], v[60:63]
	v_mfma_f32_16x16x32_bf16 v[56:59], v[162:165], v[186:189], v[56:59]
	v_mfma_f32_16x16x32_bf16 v[48:51], v[154:157], v[194:197], v[48:51]
	v_mfma_f32_16x16x32_bf16 v[40:43], v[162:165], v[194:197], v[40:43]
	v_mfma_f32_16x16x32_bf16 v[32:35], v[154:157], v[202:205], v[32:35]
	v_mfma_f32_16x16x32_bf16 v[24:27], v[162:165], v[202:205], v[24:27]
	v_mfma_f32_16x16x32_bf16 v[16:19], v[154:157], v[210:213], v[16:19]
	v_mfma_f32_16x16x32_bf16 v[8:11], v[162:165], v[210:213], v[8:11]
	v_mfma_f32_16x16x32_bf16 v[60:63], v[158:161], v[190:193], v[60:63]
	v_mfma_f32_16x16x32_bf16 v[56:59], v[166:169], v[190:193], v[56:59]
	v_mfma_f32_16x16x32_bf16 v[48:51], v[158:161], v[198:201], v[48:51]
	v_mfma_f32_16x16x32_bf16 v[40:43], v[166:169], v[198:201], v[40:43]
	v_mfma_f32_16x16x32_bf16 v[32:35], v[158:161], v[206:209], v[32:35]
	v_mfma_f32_16x16x32_bf16 v[24:27], v[166:169], v[206:209], v[24:27]
	v_mfma_f32_16x16x32_bf16 v[16:19], v[158:161], v[214:217], v[16:19]
	v_mfma_f32_16x16x32_bf16 v[8:11], v[166:169], v[214:217], v[8:11]
	s_setprio 0
	s_setprio 1
	v_mfma_f32_16x16x32_bf16 v[52:55], v[170:173], v[186:189], v[52:55]
	v_mfma_f32_16x16x32_bf16 v[44:47], v[178:181], v[186:189], v[44:47]
	v_mfma_f32_16x16x32_bf16 v[36:39], v[170:173], v[194:197], v[36:39]
	v_mfma_f32_16x16x32_bf16 v[28:31], v[178:181], v[194:197], v[28:31]
	v_mfma_f32_16x16x32_bf16 v[20:23], v[170:173], v[202:205], v[20:23]
	v_mfma_f32_16x16x32_bf16 v[12:15], v[178:181], v[202:205], v[12:15]
	v_mfma_f32_16x16x32_bf16 v[4:7], v[170:173], v[210:213], v[4:7]
	v_mfma_f32_16x16x32_bf16 v[0:3], v[178:181], v[210:213], v[0:3]
	v_mfma_f32_16x16x32_bf16 v[52:55], v[174:177], v[190:193], v[52:55]
	v_mfma_f32_16x16x32_bf16 v[44:47], v[182:185], v[190:193], v[44:47]
	v_mfma_f32_16x16x32_bf16 v[36:39], v[174:177], v[198:201], v[36:39]
	v_mfma_f32_16x16x32_bf16 v[28:31], v[182:185], v[198:201], v[28:31]
	v_mfma_f32_16x16x32_bf16 v[20:23], v[174:177], v[206:209], v[20:23]
	v_mfma_f32_16x16x32_bf16 v[12:15], v[182:185], v[206:209], v[12:15]
	v_mfma_f32_16x16x32_bf16 v[4:7], v[174:177], v[214:217], v[4:7]
	v_mfma_f32_16x16x32_bf16 v[0:3], v[182:185], v[214:217], v[0:3]
	s_setprio 0
	s_barrier
	s_add_i32 s62, s62, 2
	s_add_u32 s48, s48, 0x100
	s_addc_u32 s49, s49, 0
	s_add_u32 s56, s56, 0x100
	s_addc_u32 s57, s57, 0
